# phase_prologue w_br/w_out conversion hand-pipelined like convert_win(0) (loads before stores, counted wait skips store acks); compiler loop keeps only w_mem tiles
# baseline (speedup 1.0000x reference)
.LBB0_7:
.LBB0_8:
	s_load_dwordx2 s[30:31], s[62:63], 0xa0
	s_load_dwordx2 s[34:35], s[62:63], 0xa8
	v_lshrrev_b32_e32 v186, 7, v208
	v_and_b32_e32 v187, 0x7f, v208
	v_lshl_add_u32 v188, v186, 10, v187
	v_lshlrev_b32_e32 v132, 2, v188
	v_mov_b32_e32 v188, 0x90
	v_mul_u32_u24_e32 v188, v187, v188
	v_lshl_add_u32 v133, v186, 1, v188
	v_lshrrev_b32_e32 v186, 3, v208
	v_and_b32_e32 v188, 7, v208
	v_lshlrev_b32_e32 v187, 4, v188
	v_mov_b32_e32 v188, 0x90
	v_mul_u32_u24_e32 v188, v186, v188
	v_add_u32_e32 v134, v188, v187
	s_mov_b32 s11, s66
	s_sub_i32 s10, s64, s66
	s_waitcnt lgkmcnt(0)
	s_mov_b32 s10, s10
.Lpc_adv1:
	s_add_i32 s10, s10, s11
	s_cmpk_lt_u32 s10, 0x780
	s_cbranch_scc0 .Lpc_done
	s_cmpk_ge_u32 s10, 0x1e0
	s_cselect_b32 s20, 1, 0
	s_cmpk_ge_u32 s10, 0x3c0
	s_cselect_b32 s22, 1, 0
	s_add_i32 s20, s20, s22
	s_cmpk_ge_u32 s10, 0x5a0
	s_cselect_b32 s22, 1, 0
	s_add_i32 s20, s20, s22
	s_mul_i32 s22, s20, 0x1e0
	s_sub_i32 s21, s10, s22
	s_cmpk_lt_u32 s21, 0x1a0
	s_cbranch_scc0 .Lpc_adv1
	s_cmpk_ge_u32 s10, 0x1e0
	s_cselect_b32 s20, 1, 0
	s_cmpk_ge_u32 s10, 0x3c0
	s_cselect_b32 s22, 1, 0
	s_add_i32 s20, s20, s22
	s_cmpk_ge_u32 s10, 0x5a0
	s_cselect_b32 s22, 1, 0
	s_add_i32 s20, s20, s22
	s_mul_i32 s22, s20, 0x1e0
	s_sub_i32 s21, s10, s22
	s_cmpk_lt_u32 s21, 0x100
	s_cbranch_scc0 .Lpc_b2
	s_lshr_b32 s22, s21, 6
	s_lshl_b32 s22, s22, 19
	s_and_b32 s1, s21, 63
	s_and_b32 s2, s1, 7
	s_lshr_b32 s1, s1, 3
	s_movk_i32 s23, 0x200
	s_mov_b32 s3, 0
	s_mul_i32 s21, s20, 0x240000
	s_add_i32 s22, s22, s21
	s_branch .Lpc_e2
.Lpc_b2:
	s_cmpk_lt_u32 s21, 0x120
	s_cbranch_scc0 .Lpc_c2
	s_sub_i32 s1, s21, 0x100
	s_and_b32 s2, s1, 3
	s_lshr_b32 s1, s1, 2
	s_movk_i32 s23, 0x100
	s_mov_b32 s3, 0
	s_mul_i32 s22, s20, 0x240000
	s_add_i32 s22, s22, 0x200000
	s_branch .Lpc_e2
.Lpc_c2:
	s_sub_i32 s1, s21, 0x120
	s_and_b32 s2, s1, 15
	s_lshr_b32 s1, s1, 4
	s_movk_i32 s23, 0x400
	s_mov_b32 s3, 1
	s_lshl_b32 s22, s20, 20
.Lpc_e2:
	s_lshl_b32 s1, s1, 7
	s_lshl_b32 s2, s2, 6
	s_lshl_b32 s21, s2, 10
	s_add_i32 s21, s21, s1
	s_add_i32 s21, s21, s22
	s_lshl_b32 s21, s21, 2
	s_cmp_eq_u32 s3, 0
	s_cselect_b32 s12, s30, s34
	s_cselect_b32 s13, s31, s35
	s_add_u32 s12, s12, s21
	s_addc_u32 s13, s13, 0
	s_mov_b64 s[14:15], s[12:13]
	global_load_dword v136, v132, s[14:15]
	s_add_u32 s14, s14, 0x4000
	s_addc_u32 s15, s15, 0
	global_load_dword v137, v132, s[14:15]
	s_add_u32 s14, s14, 0x4000
	s_addc_u32 s15, s15, 0
	global_load_dword v138, v132, s[14:15]
	s_add_u32 s14, s14, 0x4000
	s_addc_u32 s15, s15, 0
	global_load_dword v139, v132, s[14:15]
	s_add_u32 s14, s14, 0x4000
	s_addc_u32 s15, s15, 0
	global_load_dword v140, v132, s[14:15]
	s_add_u32 s14, s14, 0x4000
	s_addc_u32 s15, s15, 0
	global_load_dword v141, v132, s[14:15]
	s_add_u32 s14, s14, 0x4000
	s_addc_u32 s15, s15, 0
	global_load_dword v142, v132, s[14:15]
	s_add_u32 s14, s14, 0x4000
	s_addc_u32 s15, s15, 0
	global_load_dword v143, v132, s[14:15]
	s_add_u32 s14, s14, 0x4000
	s_addc_u32 s15, s15, 0
	global_load_dword v144, v132, s[14:15]
	s_add_u32 s14, s14, 0x4000
	s_addc_u32 s15, s15, 0
	global_load_dword v145, v132, s[14:15]
	s_add_u32 s14, s14, 0x4000
	s_addc_u32 s15, s15, 0
	global_load_dword v146, v132, s[14:15]
	s_add_u32 s14, s14, 0x4000
	s_addc_u32 s15, s15, 0
	global_load_dword v147, v132, s[14:15]
	s_add_u32 s14, s14, 0x4000
	s_addc_u32 s15, s15, 0
	global_load_dword v148, v132, s[14:15]
	s_add_u32 s14, s14, 0x4000
	s_addc_u32 s15, s15, 0
	global_load_dword v149, v132, s[14:15]
	s_add_u32 s14, s14, 0x4000
	s_addc_u32 s15, s15, 0
	global_load_dword v150, v132, s[14:15]
	s_add_u32 s14, s14, 0x4000
	s_addc_u32 s15, s15, 0
	global_load_dword v151, v132, s[14:15]
	s_mov_b32 s27, 0
.Lpc_loop:
	s_mov_b32 s28, s10
.Lpc_adv3:
	s_add_i32 s28, s28, s11
	s_cmpk_lt_u32 s28, 0x780
	s_cbranch_scc0 .Lpc_nonext0
	s_cmpk_ge_u32 s28, 0x1e0
	s_cselect_b32 s20, 1, 0
	s_cmpk_ge_u32 s28, 0x3c0
	s_cselect_b32 s22, 1, 0
	s_add_i32 s20, s20, s22
	s_cmpk_ge_u32 s28, 0x5a0
	s_cselect_b32 s22, 1, 0
	s_add_i32 s20, s20, s22
	s_mul_i32 s22, s20, 0x1e0
	s_sub_i32 s21, s28, s22
	s_cmpk_lt_u32 s21, 0x1a0
	s_cbranch_scc0 .Lpc_adv3
	s_cmpk_ge_u32 s28, 0x1e0
	s_cselect_b32 s20, 1, 0
	s_cmpk_ge_u32 s28, 0x3c0
	s_cselect_b32 s22, 1, 0
	s_add_i32 s20, s20, s22
	s_cmpk_ge_u32 s28, 0x5a0
	s_cselect_b32 s22, 1, 0
	s_add_i32 s20, s20, s22
	s_mul_i32 s22, s20, 0x1e0
	s_sub_i32 s21, s28, s22
	s_cmpk_lt_u32 s21, 0x100
	s_cbranch_scc0 .Lpc_b4
	s_lshr_b32 s22, s21, 6
	s_lshl_b32 s22, s22, 19
	s_and_b32 s1, s21, 63
	s_and_b32 s2, s1, 7
	s_lshr_b32 s1, s1, 3
	s_movk_i32 s23, 0x200
	s_mov_b32 s3, 0
	s_mul_i32 s21, s20, 0x240000
	s_add_i32 s22, s22, s21
	s_branch .Lpc_e4

.Lpc_e4:
	s_lshl_b32 s1, s1, 7
	s_lshl_b32 s2, s2, 6
	s_lshl_b32 s21, s2, 10
	s_add_i32 s21, s21, s1
	s_add_i32 s21, s21, s22
	s_lshl_b32 s21, s21, 2
	s_cmp_eq_u32 s3, 0
	s_cselect_b32 s12, s30, s34
	s_cselect_b32 s13, s31, s35
	s_add_u32 s12, s12, s21
	s_addc_u32 s13, s13, 0
	s_mov_b64 s[14:15], s[12:13]
	global_load_dword v170, v132, s[14:15]
	s_add_u32 s14, s14, 0x4000
	s_addc_u32 s15, s15, 0
	global_load_dword v171, v132, s[14:15]
	s_add_u32 s14, s14, 0x4000
	s_addc_u32 s15, s15, 0
	global_load_dword v172, v132, s[14:15]
	s_add_u32 s14, s14, 0x4000
	s_addc_u32 s15, s15, 0
	global_load_dword v173, v132, s[14:15]
	s_add_u32 s14, s14, 0x4000
	s_addc_u32 s15, s15, 0
	global_load_dword v174, v132, s[14:15]
	s_add_u32 s14, s14, 0x4000
	s_addc_u32 s15, s15, 0
	global_load_dword v175, v132, s[14:15]
	s_add_u32 s14, s14, 0x4000
	s_addc_u32 s15, s15, 0
	global_load_dword v176, v132, s[14:15]
	s_add_u32 s14, s14, 0x4000
	s_addc_u32 s15, s15, 0
	global_load_dword v177, v132, s[14:15]
	s_add_u32 s14, s14, 0x4000
	s_addc_u32 s15, s15, 0
	global_load_dword v178, v132, s[14:15]
	s_add_u32 s14, s14, 0x4000
	s_addc_u32 s15, s15, 0
	global_load_dword v179, v132, s[14:15]
	s_add_u32 s14, s14, 0x4000
	s_addc_u32 s15, s15, 0
	global_load_dword v180, v132, s[14:15]
	s_add_u32 s14, s14, 0x4000
	s_addc_u32 s15, s15, 0
	global_load_dword v181, v132, s[14:15]
	s_add_u32 s14, s14, 0x4000
	s_addc_u32 s15, s15, 0
	global_load_dword v182, v132, s[14:15]
	s_add_u32 s14, s14, 0x4000
	s_addc_u32 s15, s15, 0
	global_load_dword v183, v132, s[14:15]
	s_add_u32 s14, s14, 0x4000
	s_addc_u32 s15, s15, 0
	global_load_dword v184, v132, s[14:15]
	s_add_u32 s14, s14, 0x4000
	s_addc_u32 s15, s15, 0
	global_load_dword v185, v132, s[14:15]
	s_cmp_eq_u32 s27, 0
	s_cbranch_scc1 .Lpc_first0
	s_waitcnt vmcnt(18)
	s_branch .Lpc_proc0

.Lpc_nonext0:
	s_waitcnt vmcnt(0)
	s_movk_i32 s28, 0x780
.Lpc_proc0:
	v_cvt_pk_bf16_f32 v136, v136, v136
	v_cvt_pk_bf16_f32 v137, v137, v137
	v_cvt_pk_bf16_f32 v138, v138, v138
	v_cvt_pk_bf16_f32 v139, v139, v139
	v_cvt_pk_bf16_f32 v140, v140, v140
	v_cvt_pk_bf16_f32 v141, v141, v141
	v_cvt_pk_bf16_f32 v142, v142, v142
	v_cvt_pk_bf16_f32 v143, v143, v143
	v_cvt_pk_bf16_f32 v144, v144, v144
	v_cvt_pk_bf16_f32 v145, v145, v145
	v_cvt_pk_bf16_f32 v146, v146, v146
	v_cvt_pk_bf16_f32 v147, v147, v147
	v_cvt_pk_bf16_f32 v148, v148, v148
	v_cvt_pk_bf16_f32 v149, v149, v149
	v_cvt_pk_bf16_f32 v150, v150, v150
	v_cvt_pk_bf16_f32 v151, v151, v151
	ds_write_b16 v133, v136 offset:0
	ds_write_b16 v133, v137 offset:8
	ds_write_b16 v133, v138 offset:16
	ds_write_b16 v133, v139 offset:24
	ds_write_b16 v133, v140 offset:32
	ds_write_b16 v133, v141 offset:40
	ds_write_b16 v133, v142 offset:48
	ds_write_b16 v133, v143 offset:56
	ds_write_b16 v133, v144 offset:64
	ds_write_b16 v133, v145 offset:72
	ds_write_b16 v133, v146 offset:80
	ds_write_b16 v133, v147 offset:88
	ds_write_b16 v133, v148 offset:96
	ds_write_b16 v133, v149 offset:104
	ds_write_b16 v133, v150 offset:112
	ds_write_b16 v133, v151 offset:120
	s_cmpk_ge_u32 s10, 0x1e0
	s_cselect_b32 s20, 1, 0
	s_cmpk_ge_u32 s10, 0x3c0
	s_cselect_b32 s22, 1, 0
	s_add_i32 s20, s20, s22
	s_cmpk_ge_u32 s10, 0x5a0
	s_cselect_b32 s22, 1, 0
	s_add_i32 s20, s20, s22
	s_mul_i32 s22, s20, 0x1e0
	s_sub_i32 s21, s10, s22
	s_cmpk_lt_u32 s21, 0x100
	s_cbranch_scc0 .Lpc_b5
	s_lshr_b32 s22, s21, 6
	s_lshl_b32 s22, s22, 19
	s_and_b32 s1, s21, 63
	s_and_b32 s2, s1, 7
	s_lshr_b32 s1, s1, 3
	s_movk_i32 s23, 0x200
	s_mov_b32 s3, 0
	s_mul_i32 s21, s20, 0x240000
	s_add_i32 s22, s22, s21
	s_branch .Lpc_e5

.Lpc_e5:
	s_lshl_b32 s1, s1, 7
	s_lshl_b32 s2, s2, 6
	s_mul_i32 s21, s1, s23
	s_add_i32 s21, s21, s2
	s_add_i32 s21, s21, s22
	s_lshl_b32 s21, s21, 1
	s_mov_b32 s22, 0x3100000
	s_cmp_eq_u32 s3, 0
	s_cselect_b32 s22, s22, 0x4300000
	s_add_u32 s16, s8, s22
	s_addc_u32 s17, s9, 0
	s_add_u32 s16, s16, s21
	s_addc_u32 s17, s17, 0
	s_lshl_b32 s23, s23, 1
	s_lshl_b32 s22, s23, 6
	s_add_u32 s18, s16, s22
	s_addc_u32 s19, s17, 0
	v_mad_u32_u24 v135, v186, s23, v187
	s_waitcnt lgkmcnt(0)
	s_barrier
	ds_read_b128 v[210:213], v134 offset:0
	ds_read_b128 v[214:217], v134 offset:9216
	s_waitcnt lgkmcnt(1)
	global_store_dwordx4 v135, v[210:213], s[16:17]
	s_waitcnt lgkmcnt(0)
	global_store_dwordx4 v135, v[214:217], s[18:19]
	s_mov_b32 s10, s28
	s_cmpk_lt_u32 s10, 0x780
	s_cbranch_scc0 .Lpc_done
	s_mov_b32 s28, s10

.Lpc_e7:
	s_lshl_b32 s1, s1, 7
	s_lshl_b32 s2, s2, 6
	s_lshl_b32 s21, s2, 10
	s_add_i32 s21, s21, s1
	s_add_i32 s21, s21, s22
	s_lshl_b32 s21, s21, 2
	s_cmp_eq_u32 s3, 0
	s_cselect_b32 s12, s30, s34
	s_cselect_b32 s13, s31, s35
	s_add_u32 s12, s12, s21
	s_addc_u32 s13, s13, 0
	s_mov_b64 s[14:15], s[12:13]
	global_load_dword v136, v132, s[14:15]
	s_add_u32 s14, s14, 0x4000
	s_addc_u32 s15, s15, 0
	global_load_dword v137, v132, s[14:15]
	s_add_u32 s14, s14, 0x4000
	s_addc_u32 s15, s15, 0
	global_load_dword v138, v132, s[14:15]
	s_add_u32 s14, s14, 0x4000
	s_addc_u32 s15, s15, 0
	global_load_dword v139, v132, s[14:15]
	s_add_u32 s14, s14, 0x4000
	s_addc_u32 s15, s15, 0
	global_load_dword v140, v132, s[14:15]
	s_add_u32 s14, s14, 0x4000
	s_addc_u32 s15, s15, 0
	global_load_dword v141, v132, s[14:15]
	s_add_u32 s14, s14, 0x4000
	s_addc_u32 s15, s15, 0
	global_load_dword v142, v132, s[14:15]
	s_add_u32 s14, s14, 0x4000
	s_addc_u32 s15, s15, 0
	global_load_dword v143, v132, s[14:15]
	s_add_u32 s14, s14, 0x4000
	s_addc_u32 s15, s15, 0
	global_load_dword v144, v132, s[14:15]
	s_add_u32 s14, s14, 0x4000
	s_addc_u32 s15, s15, 0
	global_load_dword v145, v132, s[14:15]
	s_add_u32 s14, s14, 0x4000
	s_addc_u32 s15, s15, 0
	global_load_dword v146, v132, s[14:15]
	s_add_u32 s14, s14, 0x4000
	s_addc_u32 s15, s15, 0
	global_load_dword v147, v132, s[14:15]
	s_add_u32 s14, s14, 0x4000
	s_addc_u32 s15, s15, 0
	global_load_dword v148, v132, s[14:15]
	s_add_u32 s14, s14, 0x4000
	s_addc_u32 s15, s15, 0
	global_load_dword v149, v132, s[14:15]
	s_add_u32 s14, s14, 0x4000
	s_addc_u32 s15, s15, 0
	global_load_dword v150, v132, s[14:15]
	s_add_u32 s14, s14, 0x4000
	s_addc_u32 s15, s15, 0
	global_load_dword v151, v132, s[14:15]
	s_cmp_eq_u32 s27, 0
	s_cbranch_scc1 .Lpc_first1
	s_waitcnt vmcnt(18)
	s_branch .Lpc_proc1

.Lpc_proc1:
	v_cvt_pk_bf16_f32 v170, v170, v170
	v_cvt_pk_bf16_f32 v171, v171, v171
	v_cvt_pk_bf16_f32 v172, v172, v172
	v_cvt_pk_bf16_f32 v173, v173, v173
	v_cvt_pk_bf16_f32 v174, v174, v174
	v_cvt_pk_bf16_f32 v175, v175, v175
	v_cvt_pk_bf16_f32 v176, v176, v176
	v_cvt_pk_bf16_f32 v177, v177, v177
	v_cvt_pk_bf16_f32 v178, v178, v178
	v_cvt_pk_bf16_f32 v179, v179, v179
	v_cvt_pk_bf16_f32 v180, v180, v180
	v_cvt_pk_bf16_f32 v181, v181, v181
	v_cvt_pk_bf16_f32 v182, v182, v182
	v_cvt_pk_bf16_f32 v183, v183, v183
	v_cvt_pk_bf16_f32 v184, v184, v184
	v_cvt_pk_bf16_f32 v185, v185, v185
	ds_write_b16 v133, v170 offset:18432
	ds_write_b16 v133, v171 offset:18440
	ds_write_b16 v133, v172 offset:18448
	ds_write_b16 v133, v173 offset:18456
	ds_write_b16 v133, v174 offset:18464
	ds_write_b16 v133, v175 offset:18472
	ds_write_b16 v133, v176 offset:18480
	ds_write_b16 v133, v177 offset:18488
	ds_write_b16 v133, v178 offset:18496
	ds_write_b16 v133, v179 offset:18504
	ds_write_b16 v133, v180 offset:18512
	ds_write_b16 v133, v181 offset:18520
	ds_write_b16 v133, v182 offset:18528
	ds_write_b16 v133, v183 offset:18536
	ds_write_b16 v133, v184 offset:18544
	ds_write_b16 v133, v185 offset:18552
	s_cmpk_ge_u32 s10, 0x1e0
	s_cselect_b32 s20, 1, 0
	s_cmpk_ge_u32 s10, 0x3c0
	s_cselect_b32 s22, 1, 0
	s_add_i32 s20, s20, s22
	s_cmpk_ge_u32 s10, 0x5a0
	s_cselect_b32 s22, 1, 0
	s_add_i32 s20, s20, s22
	s_mul_i32 s22, s20, 0x1e0
	s_sub_i32 s21, s10, s22
	s_cmpk_lt_u32 s21, 0x100
	s_cbranch_scc0 .Lpc_b8
	s_lshr_b32 s22, s21, 6
	s_lshl_b32 s22, s22, 19
	s_and_b32 s1, s21, 63
	s_and_b32 s2, s1, 7
	s_lshr_b32 s1, s1, 3
	s_movk_i32 s23, 0x200
	s_mov_b32 s3, 0
	s_mul_i32 s21, s20, 0x240000
	s_add_i32 s22, s22, s21
	s_branch .Lpc_e8

.Lpc_e8:
	s_lshl_b32 s1, s1, 7
	s_lshl_b32 s2, s2, 6
	s_mul_i32 s21, s1, s23
	s_add_i32 s21, s21, s2
	s_add_i32 s21, s21, s22
	s_lshl_b32 s21, s21, 1
	s_mov_b32 s22, 0x3100000
	s_cmp_eq_u32 s3, 0
	s_cselect_b32 s22, s22, 0x4300000
	s_add_u32 s16, s8, s22
	s_addc_u32 s17, s9, 0
	s_add_u32 s16, s16, s21
	s_addc_u32 s17, s17, 0
	s_lshl_b32 s23, s23, 1
	s_lshl_b32 s22, s23, 6
	s_add_u32 s18, s16, s22
	s_addc_u32 s19, s17, 0
	v_mad_u32_u24 v135, v186, s23, v187
	s_waitcnt lgkmcnt(0)
	s_barrier
	ds_read_b128 v[210:213], v134 offset:18432
	ds_read_b128 v[214:217], v134 offset:27648
	s_waitcnt lgkmcnt(1)
	global_store_dwordx4 v135, v[210:213], s[16:17]
	s_waitcnt lgkmcnt(0)
	global_store_dwordx4 v135, v[214:217], s[18:19]
	s_mov_b32 s10, s28
	s_cmpk_lt_u32 s10, 0x780
	s_cbranch_scc0 .Lpc_done
	s_branch .Lpc_loop
.Lpc_done:
	s_waitcnt lgkmcnt(0)
	s_barrier
	v_mov_b32_e32 v19, 0
	global_load_dwordx4 v[2:5], v19, s[6:7] offset:144
	global_load_dwordx4 v[6:9], v19, s[6:7] offset:160
	s_add_u32 s1, s8, 0x3100000
	s_addc_u32 s3, s9, 0
	s_add_u32 s14, s8, 0x4300000
	s_addc_u32 s15, s9, 0
	s_add_u32 s16, s8, 0x78c2800
	s_addc_u32 s17, s9, 0
	s_lshl_b32 s21, s64, 3
	s_movk_i32 s2, 0x90
	s_lshl_b32 s18, s64, 6
	s_lshl_b32 s19, s66, 6
	s_lshl_b32 s20, s66, 3
	v_writelane_b32 v253, s21, 2
	s_mov_b32 s22, s64
	s_waitcnt vmcnt(1)
	v_cmp_ne_u64_e32 vcc, 0, v[2:3]
	s_nop 1
	v_cndmask_b32_e64 v1, 0, 1, vcc
	v_cmp_ne_u32_e64 s[6:7], 1, v1
	s_branch .LBB0_12
